# stagger 1 sleep (~3.5 us)
# baseline (speedup 1.0000x reference)
.LBB0_539:
	s_or_b64 exec, exec, s[0:1]
	v_mov_b32_e32 v0, v154
	v_readlane_b32 s6, v253, 0
	s_waitcnt lgkmcnt(0)
	s_barrier
	v_readlane_b32 s8, v253, 0
	s_bitcmp1_b32 s8, 0
	s_cbranch_scc0 .Lstag_skip
	s_sleep 127
.Lstag_skip:
	s_cmpk_gt_i32 s6, 0xff
	s_cbranch_scc1 .LBB0_546
	v_readlane_b32 s0, v254, 24
	v_readlane_b32 s1, v254, 60
	s_add_u32 s7, s0, s1
	v_readlane_b32 s0, v254, 25
	s_addc_u32 s8, s0, 0
	s_lshl_b32 s9, s6, 3
	s_branch .LBB0_542
